# plus: unit prologues issue the loads of their first two key tiles (and FoX forget-bias values) together
# speedup vs baseline: 1.0389x; 1.0053x over previous
.LBB0_644:
	s_lshl_b32 s56, s14, 6
	s_lshl_b32 s4, s52, 10
	v_readlane_b32 s5, v253, 60
	s_add_u32 s4, s5, s4
	v_readlane_b32 s5, v253, 61
	s_waitcnt lgkmcnt(0)
	s_barrier
	ds_read_b32 v12, v13 offset:43520
	s_addc_u32 s5, s5, 0
	s_lshl_b32 s16, s56, 1
	s_add_u32 s12, s4, s16
	s_addc_u32 s13, s5, 0
	s_lshl_b32 s25, s11, 15
	s_lshl_b32 s57, s14, 12
	s_or_b32 s4, s25, s57
	s_lshl_b32 s4, s4, 2
	v_readlane_b32 s6, v253, 44
	s_waitcnt lgkmcnt(0)
	v_readfirstlane_b32 s10, v12
	v_readlane_b32 s7, v253, 45
	s_add_u32 s4, s6, s4
	s_addc_u32 s5, s7, 0
	s_ashr_i32 s11, s10, 31
	v_and_b32_e32 v24, 7, v18
	s_lshl_b64 s[6:7], s[10:11], 16
	v_ashrrev_i32_e32 v23, 3, v19
	v_lshlrev_b32_e32 v12, 3, v24
	s_add_u32 s6, s12, s6
	v_lshl_or_b32 v12, v23, 9, v12
	s_addc_u32 s7, s13, s7
	v_lshl_add_u64 v[14:15], v[12:13], 1, s[6:7]
	s_barrier
	global_load_dwordx4 v[14:17], v[14:15], off
	v_cmp_gt_i32_e64 s[6:7], 64, v19
	v_mov_b32_e32 v152, 0
	v_lshlrev_b32_e32 v140, 2, v22
	s_and_saveexec_b64 s[14:15], s[6:7]
	s_cbranch_execz .LBB0_646
	s_lshl_b64 s[26:27], s[10:11], 8
	s_add_u32 s26, s4, s26
	s_addc_u32 s27, s5, s27
	global_load_dword v152, v140, s[26:27]
.LBB0_646:
	s_or_b64 exec, exec, s[14:15]
	s_lshl_b32 s14, s52, 9
	s_lshl_b64 s[26:27], s[10:11], 15
	s_movk_i32 s11, 0x90
	v_mul_lo_u32 v22, v23, s11
	s_lshl_b32 s11, s14, 1
	v_readlane_b32 s14, v253, 58
	s_add_u32 s11, s14, s11
	v_readlane_b32 s14, v253, 59
	s_addc_u32 s15, s14, 0
	v_ashrrev_i32_e32 v23, 8, v19
	s_add_u32 s14, s11, s16
	v_lshl_add_u32 v162, v24, 4, v22
	v_bfe_u32 v24, v19, 2, 6
	s_addc_u32 s15, s15, 0
	v_lshlrev_b32_e32 v25, 5, v23
	s_lshl_b64 s[16:17], s[26:27], 1
	v_and_b32_e32 v22, 3, v18
	v_lshl_add_u32 v25, v24, 9, v25
	s_add_u32 s16, s14, s16
	v_lshl_or_b32 v144, v22, 3, v25
	s_addc_u32 s17, s15, s17
	v_mov_b32_e32 v145, v13
	v_lshl_add_u64 v[26:27], v[144:145], 1, s[16:17]
	global_load_dwordx4 v[118:121], v[26:27], off
	s_add_i32 s52, s10, 1
	s_ashr_i32 s53, s52, 31
	s_lshl_b64 s[54:55], s[52:53], 16
	s_add_u32 s54, s12, s54
	s_addc_u32 s55, s13, s55
	v_lshl_add_u64 v[192:193], v[12:13], 1, s[54:55]
	global_load_dwordx4 v[114:117], v[192:193], off
	s_and_saveexec_b64 s[54:55], s[6:7]
	s_cbranch_execz .Lfpro_nock1
	s_lshl_b64 s[16:17], s[52:53], 8
	s_add_u32 s16, s4, s16
	s_addc_u32 s17, s5, s17
	global_load_dword v195, v140, s[16:17]
.Lfpro_nock1:
	s_or_b64 exec, exec, s[54:55]
	v_add_u32_e32 v153, 0, v162
	v_lshl_add_u32 v154, v19, 2, 0
	s_waitcnt vmcnt(2)
	ds_write_b128 v153, v[14:17]
	s_and_saveexec_b64 s[52:53], s[6:7]
	v_xor_b32_e32 v152, 0x80000000, v152
	ds_write_b32 v154, v152 offset:43008
	s_or_b64 exec, exec, s[52:53]
	s_add_i32 s52, s10, 1
	s_ashr_i32 s53, s52, 31
	s_lshl_b64 s[16:17], s[52:53], 16
	s_add_u32 s16, s12, s16
	v_lshlrev_b32_e32 v14, 12, v23
	v_lshlrev_b32_e32 v15, 6, v24
	v_lshl_add_u32 v16, v22, 4, 0
	s_addc_u32 s17, s13, s17
	v_add3_u32 v155, v16, v14, v15
	v_lshl_add_u64 v[14:15], v[12:13], 1, s[16:17]
	s_waitcnt vmcnt(1)
	ds_write_b128 v155, v[118:121] offset:26624
	s_and_saveexec_b64 s[54:55], s[6:7]
	s_cbranch_execz .LBB0_650
	s_lshl_b64 s[16:17], s[52:53], 8
	s_add_u32 s16, s4, s16
	s_addc_u32 s17, s5, s17
.LBB0_650:
	s_or_b64 exec, exec, s[54:55]
	s_waitcnt vmcnt(0)
	ds_write_b128 v153, v[114:117] offset:13312
	s_and_saveexec_b64 s[52:53], s[6:7]
	v_xor_b32_e32 v152, 0x80000000, v195
	ds_write_b32 v154, v152 offset:43264
	s_or_b64 exec, exec, s[52:53]
	s_and_b32 s55, s10, 1
	s_lshl_b32 s11, s55, 8
	s_add_i32 s52, s11, 0
	s_mul_i32 s16, s55, 0x3300
	v_add_u32_e32 v26, s52, v30
	s_add_i32 s52, s52, s16
	v_mov_b32_e32 v14, s52
	s_movk_i32 s16, 0x90
	v_mad_u32_u24 v14, v20, s16, v14
	v_add_u32_e32 v163, v14, v30
	s_waitcnt lgkmcnt(0)
	s_barrier
	ds_read_b128 v[190:193], v163
	ds_read_b128 v[46:49], v26 offset:43008
	ds_read_b128 v[50:53], v26 offset:43040
	ds_read_b128 v[54:57], v26 offset:43072
	ds_read_b128 v[58:61], v26 offset:43104
	ds_read_b128 v[198:201], v163 offset:4608
	ds_read_b128 v[62:65], v26 offset:43136
	ds_read_b128 v[66:69], v26 offset:43168
	ds_read_b128 v[70:73], v26 offset:43200
	ds_read_b128 v[74:77], v26 offset:43232
	ds_read_b128 v[194:197], v163 offset:32
	ds_read_b128 v[202:205], v163 offset:4640
	ds_read_b128 v[206:209], v163 offset:64
	ds_read_b128 v[210:213], v163 offset:4672
	ds_read_b128 v[214:217], v163 offset:96
	s_waitcnt lgkmcnt(10)
	v_mfma_f32_32x32x16_bf16 v[46:61], v[190:193], v[0:3], v[46:61]
	ds_read_b128 v[222:225], v163 offset:4704
	s_lshl_b32 s16, s10, 6
	s_or_b32 s17, s16, 63
	v_lshlrev_b32_e32 v156, 2, v21
	s_cmp_le_i32 s17, s40
	v_or_b32_e32 v157, s40, v20
	s_waitcnt lgkmcnt(5)
	v_mfma_f32_32x32x16_bf16 v[46:61], v[194:197], v[4:7], v[46:61]
	s_waitcnt lgkmcnt(6)
	v_mfma_f32_32x32x16_bf16 v[62:77], v[198:201], v[0:3], v[62:77]
	s_waitcnt lgkmcnt(4)
	v_mfma_f32_32x32x16_bf16 v[62:77], v[202:205], v[4:7], v[62:77]
	s_waitcnt lgkmcnt(3)
	v_mfma_f32_32x32x16_bf16 v[46:61], v[206:209], v[8:11], v[46:61]
	s_waitcnt lgkmcnt(2)
	v_mfma_f32_32x32x16_bf16 v[62:77], v[210:213], v[8:11], v[62:77]
	s_waitcnt lgkmcnt(1)
	v_mfma_f32_32x32x16_bf16 v[46:61], v[214:217], v[110:113], v[46:61]
	s_waitcnt lgkmcnt(0)
	v_mfma_f32_32x32x16_bf16 v[62:77], v[222:225], v[110:113], v[62:77]
	s_cbranch_scc1 .LBB0_654
	v_or_b32_e32 v14, s16, v156
	v_or_b32_e32 v15, 32, v14
	v_cmp_le_i32_e32 vcc, v15, v157
	v_or_b32_e32 v15, 33, v14
	s_nop 6
	v_cndmask_b32_e32 v62, v220, v62, vcc
	v_cmp_lt_i32_e32 vcc, v14, v157
	s_nop 1
	v_cndmask_b32_e32 v47, v220, v47, vcc
	v_cmp_le_i32_e32 vcc, v14, v157
	s_nop 1
	v_cndmask_b32_e32 v46, v220, v46, vcc
	v_cmp_le_i32_e32 vcc, v15, v157
	v_or_b32_e32 v15, 2, v14
	s_nop 0
	v_cndmask_b32_e32 v63, v220, v63, vcc
	v_cmp_le_i32_e32 vcc, v15, v157
	v_or_b32_e32 v15, 34, v14
	s_nop 0
	v_cndmask_b32_e32 v48, v220, v48, vcc
	v_cmp_le_i32_e32 vcc, v15, v157
	v_or_b32_e32 v15, 3, v14
	s_nop 0
	v_cndmask_b32_e32 v64, v220, v64, vcc
	v_cmp_le_i32_e32 vcc, v15, v157
	v_or_b32_e32 v15, 35, v14
	s_nop 0
	v_cndmask_b32_e32 v49, v220, v49, vcc
	v_cmp_le_i32_e32 vcc, v15, v157
	v_or_b32_e32 v15, 8, v14
	s_nop 0
	v_cndmask_b32_e32 v65, v220, v65, vcc
	v_cmp_le_i32_e32 vcc, v15, v157
	v_or_b32_e32 v15, 40, v14
	s_nop 0
	v_cndmask_b32_e32 v50, v220, v50, vcc
	v_cmp_le_i32_e32 vcc, v15, v157
	v_or_b32_e32 v15, 9, v14
	s_nop 0
	v_cndmask_b32_e32 v66, v220, v66, vcc
	v_cmp_le_i32_e32 vcc, v15, v157
	v_or_b32_e32 v15, 41, v14
	s_nop 0
	v_cndmask_b32_e32 v51, v220, v51, vcc
	v_cmp_le_i32_e32 vcc, v15, v157
	v_or_b32_e32 v15, 10, v14
	s_nop 0
	v_cndmask_b32_e32 v67, v220, v67, vcc
	v_cmp_le_i32_e32 vcc, v15, v157
	v_or_b32_e32 v15, 42, v14
	s_nop 0
	v_cndmask_b32_e32 v52, v220, v52, vcc
	v_cmp_le_i32_e32 vcc, v15, v157
	v_or_b32_e32 v15, 11, v14
	s_nop 0
	v_cndmask_b32_e32 v68, v220, v68, vcc
	v_cmp_le_i32_e32 vcc, v15, v157
	v_or_b32_e32 v15, 43, v14
	s_nop 0
	v_cndmask_b32_e32 v53, v220, v53, vcc
	v_cmp_le_i32_e32 vcc, v15, v157
	v_or_b32_e32 v15, 16, v14
	s_nop 0
	v_cndmask_b32_e32 v69, v220, v69, vcc
	v_cmp_le_i32_e32 vcc, v15, v157
	v_or_b32_e32 v15, 48, v14
	s_nop 0
	v_cndmask_b32_e32 v54, v220, v54, vcc
	v_cmp_le_i32_e32 vcc, v15, v157
	v_or_b32_e32 v15, 17, v14
	s_nop 0
	v_cndmask_b32_e32 v70, v220, v70, vcc
	v_cmp_le_i32_e32 vcc, v15, v157
	v_or_b32_e32 v15, 49, v14
	s_nop 0
	v_cndmask_b32_e32 v55, v220, v55, vcc
	v_cmp_le_i32_e32 vcc, v15, v157
	v_or_b32_e32 v15, 18, v14
	s_nop 0
	v_cndmask_b32_e32 v71, v220, v71, vcc
	v_cmp_le_i32_e32 vcc, v15, v157
	v_or_b32_e32 v15, 50, v14
	s_nop 0
	v_cndmask_b32_e32 v56, v220, v56, vcc
	v_cmp_le_i32_e32 vcc, v15, v157
	v_or_b32_e32 v15, 19, v14
	s_nop 0
	v_cndmask_b32_e32 v72, v220, v72, vcc
	v_cmp_le_i32_e32 vcc, v15, v157
	v_or_b32_e32 v15, 51, v14
	s_nop 0
	v_cndmask_b32_e32 v57, v220, v57, vcc
	v_cmp_le_i32_e32 vcc, v15, v157
	v_or_b32_e32 v15, 24, v14
	s_nop 0
	v_cndmask_b32_e32 v73, v220, v73, vcc
	v_cmp_le_i32_e32 vcc, v15, v157
	v_or_b32_e32 v15, 56, v14
	s_nop 0
	v_cndmask_b32_e32 v58, v220, v58, vcc
	v_cmp_le_i32_e32 vcc, v15, v157
	v_or_b32_e32 v15, 25, v14
	s_nop 0
	v_cndmask_b32_e32 v74, v220, v74, vcc
	v_cmp_le_i32_e32 vcc, v15, v157
	v_or_b32_e32 v15, 57, v14
	s_nop 0
	v_cndmask_b32_e32 v59, v220, v59, vcc
	v_cmp_le_i32_e32 vcc, v15, v157
	v_or_b32_e32 v15, 26, v14
	s_nop 0
	v_cndmask_b32_e32 v75, v220, v75, vcc
	v_cmp_le_i32_e32 vcc, v15, v157
	v_or_b32_e32 v15, 58, v14
	s_nop 0
	v_cndmask_b32_e32 v60, v220, v60, vcc
	v_cmp_le_i32_e32 vcc, v15, v157
	v_or_b32_e32 v15, 27, v14
	v_or_b32_e32 v14, 59, v14
	v_cndmask_b32_e32 v76, v220, v76, vcc
	v_cmp_le_i32_e32 vcc, v15, v157
	s_nop 1
	v_cndmask_b32_e32 v61, v220, v61, vcc
	v_cmp_le_i32_e32 vcc, v14, v157
	s_nop 1
	v_cndmask_b32_e32 v77, v220, v77, vcc

.LBB0_716:
	s_or_b64 exec, exec, s[10:11]
	s_lshl_b32 s10, s14, 9
	s_movk_i32 s11, 0xd0
	s_lshl_b32 s38, s13, 6
	v_mul_lo_u32 v12, v31, s11
	v_mul_lo_u32 v14, v33, s11
	s_lshl_b32 s10, s10, 1
	v_readlane_b32 s11, v253, 62
	v_ashrrev_i32_e32 v23, 8, v30
	s_add_u32 s10, s11, s10
	v_readlane_b32 s11, v253, 63
	v_lshl_add_u32 v31, v32, 4, v12
	v_and_b32_e32 v30, 63, v33
	s_addc_u32 s11, s11, 0
	s_lshl_b32 s13, s38, 1
	v_lshlrev_b32_e32 v12, 5, v23
	s_add_u32 s10, s10, s13
	v_lshl_add_u32 v12, v30, 9, v12
	s_addc_u32 s11, s11, 0
	v_or_b32_e32 v12, v12, v26
	v_lshl_add_u64 v[32:33], v[12:13], 1, s[10:11]
	global_load_dwordx4 v[130:133], v[32:33], off
	v_add_co_u32_e32 v192, vcc, 0x10000, v24
	s_nop 1
	v_addc_co_u32_e32 v193, vcc, 0, v25, vcc
	global_load_dwordx4 v[126:129], v[192:193], off
	s_and_saveexec_b64 s[10:11], s[6:7]
	s_cbranch_execz .Lmpro_nokr1
	v_mov_b32_e32 v198, v22
	v_mov_b32_e32 v199, v13
	v_lshl_add_u64 v[198:199], v[198:199], 1, s[4:5]
	v_add_co_u32_e32 v198, vcc, 0x1000, v198
	s_nop 1
	v_addc_co_u32_e32 v199, vcc, 0, v199, vcc
	global_load_dwordx4 v[194:197], v[198:199], off
.Lmpro_nokr1:
	s_or_b64 exec, exec, s[10:11]
	v_lshlrev_b32_e32 v15, 4, v34
	v_add_u32_e32 v158, 0, v31
	s_movk_i32 s16, 0xd0
	s_waitcnt vmcnt(2)
	ds_write_b128 v158, v[16:19]
	v_add3_u32 v16, v14, v15, 0
	s_and_saveexec_b64 s[10:11], s[6:7]
	ds_write_b128 v16, v[122:125] offset:128
	s_or_b64 exec, exec, s[10:11]
	v_lshlrev_b32_e32 v17, 12, v23
	v_lshlrev_b32_e32 v18, 6, v30
	v_or3_b32 v17, v15, v17, v18
	v_add_co_u32_e32 v18, vcc, 0x10000, v24
	v_add_u32_e32 v159, 0, v17
	s_nop 0
	v_addc_co_u32_e32 v19, vcc, 0, v25, vcc
	s_waitcnt vmcnt(1)
	ds_write_b128 v159, v[130:133] offset:26624
	s_waitcnt vmcnt(0)
	ds_write_b128 v158, v[126:129] offset:13312
	s_and_saveexec_b64 s[4:5], s[6:7]
	ds_write_b128 v16, v[194:197] offset:13440
	s_or_b64 exec, exec, s[4:5]
	v_lshlrev_b32_e32 v17, 3, v28
	v_lshlrev_b32_e32 v16, 1, v28
	v_and_b32_e32 v17, 24, v17
	v_and_or_b32 v16, v16, 32, v17
	v_lshlrev_b32_e32 v160, 2, v29
	v_lshrrev_b32_e32 v17, 2, v28
	v_and_or_b32 v17, v17, 3, v160
	v_lshl_or_b32 v161, v17, 6, v16
	v_mad_u32_u24 v16, v27, s16, 0
	v_add_u32_e32 v162, v16, v20
	s_waitcnt lgkmcnt(0)
	s_barrier
	ds_read_b128 v[190:193], v162 offset:6656
	ds_read_b128 v[194:197], v162
	ds_read_b128 v[198:201], v162 offset:32
	ds_read_b128 v[202:205], v162 offset:6688
	ds_read_b128 v[206:209], v162 offset:64
	ds_read_b128 v[210:213], v162 offset:6720
	ds_read_b128 v[214:217], v162 offset:96
	ds_read_b128 v[222:225], v162 offset:6752
	ds_read_b128 v[226:229], v162 offset:128
	ds_read_b128 v[230:233], v162 offset:6784
	ds_read_b128 v[16:19], v162 offset:160
	ds_read_b128 v[22:25], v162 offset:6816
	s_waitcnt lgkmcnt(11)
	v_mfma_f32_32x32x16_bf16 v[62:77], v[190:193], v[0:3], 0
	s_add_i32 s35, s35, 4
	s_mov_b32 s52, 0
	s_cmp_eq_u32 s34, 15
	v_add_u32_e32 v163, v14, v15
	v_add_u32_e32 v150, v21, v26
	s_waitcnt lgkmcnt(10)
	v_mfma_f32_32x32x16_bf16 v[46:61], v[194:197], v[0:3], 0
	s_waitcnt lgkmcnt(9)
	v_mfma_f32_32x32x16_bf16 v[46:61], v[198:201], v[4:7], v[46:61]
	s_waitcnt lgkmcnt(8)
	v_mfma_f32_32x32x16_bf16 v[62:77], v[202:205], v[4:7], v[62:77]
	s_waitcnt lgkmcnt(7)
	v_mfma_f32_32x32x16_bf16 v[46:61], v[206:209], v[8:11], v[46:61]
	s_waitcnt lgkmcnt(6)
	v_mfma_f32_32x32x16_bf16 v[62:77], v[210:213], v[8:11], v[62:77]
	s_waitcnt lgkmcnt(5)
	v_mfma_f32_32x32x16_bf16 v[46:61], v[214:217], v[110:113], v[46:61]
	s_waitcnt lgkmcnt(4)
	v_mfma_f32_32x32x16_bf16 v[62:77], v[222:225], v[110:113], v[62:77]
	s_waitcnt lgkmcnt(3)
	v_mfma_f32_32x32x16_bf16 v[46:61], v[226:229], v[114:117], v[46:61]
	s_waitcnt lgkmcnt(2)
	v_mfma_f32_32x32x16_bf16 v[62:77], v[230:233], v[114:117], v[62:77]
	s_waitcnt lgkmcnt(0)
	s_barrier
	v_mfma_f32_32x32x16_bf16 v[46:61], v[16:19], v[118:121], v[46:61]
	v_mfma_f32_32x32x16_bf16 v[62:77], v[22:25], v[118:121], v[62:77]
	v_mov_b32_e32 v14, 0
	v_mov_b32_e32 v15, 0
	v_mov_b32_e32 v16, 0
	v_mov_b32_e32 v17, 0
	v_mov_b32_e32 v18, 0
	v_mov_b32_e32 v19, 0
	v_mov_b32_e32 v20, 0
	v_mov_b32_e32 v21, 0
	v_mov_b32_e32 v22, 0
	v_mov_b32_e32 v23, 0
	v_mov_b32_e32 v24, 0
	v_mov_b32_e32 v25, 0
	v_mov_b32_e32 v26, 0
	v_mov_b32_e32 v27, 0
	v_mov_b32_e32 v28, 0
	v_mov_b32_e32 v29, 0
	v_mov_b32_e32 v30, 0
	v_mov_b32_e32 v31, 0
	v_mov_b32_e32 v32, 0
	v_mov_b32_e32 v33, 0
	v_mov_b32_e32 v34, 0
	v_mov_b32_e32 v35, 0
	v_mov_b32_e32 v36, 0
	v_mov_b32_e32 v37, 0
	v_mov_b32_e32 v38, 0
	v_mov_b32_e32 v39, 0
	v_mov_b32_e32 v40, 0
	v_mov_b32_e32 v41, 0
	v_mov_b32_e32 v42, 0
	v_mov_b32_e32 v43, 0
	v_mov_b32_e32 v44, 0
	v_mov_b32_e32 v45, 0
	v_mov_b32_e32 v165, 0
	s_and_b32 s4, s3, 56
	s_lshl_b32 s4, s4, 19
	s_or_b32 s4, s4, s12
	s_add_u32 s54, s22, s4
	s_addc_u32 s55, s23, 0
	s_add_u32 s54, s54, 0x15a20000
	s_addc_u32 s55, s55, 0
	s_add_u32 s56, s22, s96
	s_addc_u32 s57, s23, 0
	s_add_u32 s56, s56, 0x12802000
	s_addc_u32 s57, s57, 0
	v_lshlrev_b32_e32 v226, 1, v148
	v_lshlrev_b32_e32 v227, 1, v12
	v_add_u32_e32 v227, 0x1ff0000, v227
	v_lshlrev_b32_e32 v228, 1, v150
	global_load_dwordx4 v[126:129], v226, s[54:55]
	s_and_saveexec_b64 s[4:5], s[6:7]
	s_cbranch_execz .Lm3_nokrp
	global_load_dwordx4 v[122:125], v228, s[56:57]
